# stacked on write-through stores + flat barrier poll: pipelined LDS reads in the GEMM epilogue (v048 micro set) and B2 K-fragment read-ahead
# baseline (speedup 1.0000x reference)
; template <int EPI>
; DI void gemm_tile(const Params& p, int layer, int mt, int nt, u16* sm, int wv) {
;     ...
;   if (EPI == 0) {
;     const float* ssl = p.ss + (size_t)layer * MTOK;
;     __syncthreads();
;     u16* stg = sm + (wm * 2 + wn) * (128 * LSTR);
;     if (!vtile) {
;       const float qsc = (nt < 2) ? 0.17677669529663687f * LOG2E
;                         : ((nt >= 8 && nt < 12) || nt == 18 || nt == 19) ? 0.125f * LOG2E : 1.f;
; #pragma unroll
;       for (int i = 0; i < 8; ++i) {
;         const int m = m0 + wm * 128 + 16 * i + fr;
;         const float rs = __builtin_amdgcn_rsqf(ssl[m] * (1.f / DM) + EPS) * qsc;
;         u16* d = stg + (16 * i + fr) * LSTR + 4 * fq;
; #pragma unroll
;         for (int j = 0; j < 4; ++j) {
;           u32x2 v = {pk2(acc[i][j][0] * rs, acc[i][j][1] * rs), pk2(acc[i][j][2] * rs, acc[i][j][3] * rs)};
;           *(u32x2*)(d + 16 * j) = v;
;         }
;       }
.LBB0_124:
	s_waitcnt vmcnt(8)
	v_mbcnt_lo_u32_b32 v138, -1, 0
	v_mbcnt_hi_u32_b32 v138, -1, v138
	s_lshl_b32 s21, s21, 8
	v_add_u32_e32 v0, s33, v138
	v_bfe_u32 v130, v0, 6, 21
	s_waitcnt vmcnt(7)
	v_mul_u32_u24_e32 v135, 0x4800, v130
	v_and_b32_e32 v130, 0xffffff80, v0
	v_and_b32_e32 v137, 15, v138
	v_bfe_u32 v134, v138, 4, 2
	v_bfe_u32 v131, v0, 6, 1
	s_mov_b64 s[6:7], -1
	s_andn2_b64 vcc, exec, s[4:5]
	v_add_u32_e32 v139, s21, v130
	v_lshlrev_b32_e32 v136, 4, v138
	s_barrier
	s_cbranch_vccnz .LBB0_126
	v_or_b32_e32 v132, v139, v137
	v_ashrrev_i32_e32 v133, 31, v132
	v_lshl_add_u64 v[132:133], v[132:133], 2, s[0:1]
	global_load_dword v142, v[132:133], off
	global_load_dword v150, v[132:133], off offset:64
	global_load_dword v151, v[132:133], off offset:128
	global_load_dword v152, v[132:133], off offset:192
	global_load_dword v153, v[132:133], off offset:256
	global_load_dword v154, v[132:133], off offset:320
	global_load_dword v155, v[132:133], off offset:384
	global_load_dword v156, v[132:133], off offset:448
	s_and_b32 s4, s20, 0x7ffffffc
	s_cmp_eq_u32 s4, 8
	s_cselect_b64 s[4:5], -1, 0
	s_and_b32 s6, s18, -16
	s_cmpk_eq_i32 s6, 0x90
	s_cselect_b64 s[6:7], -1, 0
	s_or_b64 vcc, s[6:7], s[4:5]
	s_cmp_gt_i32 s20, 1
	v_cndmask_b32_e32 v0, 1.0, v191, vcc
	s_cselect_b64 vcc, -1, 0
	v_cndmask_b32_e32 v0, v192, v0, vcc
	s_waitcnt vmcnt(7)
	v_mul_u32_u24_e32 v143, 0x90, v137
	v_lshlrev_b32_e32 v141, 3, v134
	v_add3_u32 v141, v135, v141, v143
	v_and_b32_e32 v140, 63, v138
	s_mov_b64 s[6:7], 0
	s_waitcnt vmcnt(0)
	v_fmamk_f32 v142, v142, 0x3a800000, v188
	v_rsq_f32_e32 v142, v142
	s_nop 0
	v_mul_f32_e32 v142, v0, v142
	v_mul_f32_e32 v144, v126, v142
	v_mul_f32_e32 v145, v127, v142
	v_mul_f32_e32 v146, v128, v142
	v_mul_f32_e32 v147, v129, v142
	v_cvt_pk_bf16_f32 v144, v144, v145
	v_cvt_pk_bf16_f32 v145, v146, v147
	v_mul_f32_e32 v146, v122, v142
	v_mul_f32_e32 v147, v123, v142
	v_mul_f32_e32 v148, v124, v142
	v_mul_f32_e32 v149, v125, v142
	v_cvt_pk_bf16_f32 v146, v146, v147
	v_cvt_pk_bf16_f32 v147, v148, v149
	ds_write2_b64 v141, v[144:145], v[146:147] offset1:4
	v_mul_f32_e32 v144, v118, v142
	v_mul_f32_e32 v145, v119, v142
	v_mul_f32_e32 v146, v120, v142
	v_mul_f32_e32 v147, v121, v142
	v_cvt_pk_bf16_f32 v144, v144, v145
	v_cvt_pk_bf16_f32 v145, v146, v147
	v_mul_f32_e32 v146, v114, v142
	v_mul_f32_e32 v147, v115, v142
	v_mul_f32_e32 v143, v117, v142
	v_mul_f32_e32 v142, v116, v142
	v_cvt_pk_bf16_f32 v146, v146, v147
	v_cvt_pk_bf16_f32 v147, v142, v143
	v_mov_b32_e32 v142, v150
	ds_write2_b64 v141, v[144:145], v[146:147] offset0:8 offset1:12
	s_waitcnt vmcnt(0)
	v_fmamk_f32 v142, v142, 0x3a800000, v188
	v_rsq_f32_e32 v142, v142
	s_nop 0
	v_mul_f32_e32 v142, v0, v142
	v_mul_f32_e32 v144, v110, v142
	v_mul_f32_e32 v145, v111, v142
	v_mul_f32_e32 v146, v112, v142
	v_mul_f32_e32 v147, v113, v142
	v_cvt_pk_bf16_f32 v144, v144, v145
	v_cvt_pk_bf16_f32 v145, v146, v147
	v_mul_f32_e32 v146, v106, v142
	v_mul_f32_e32 v147, v107, v142
	v_mul_f32_e32 v148, v108, v142
	v_mul_f32_e32 v149, v109, v142
	v_cvt_pk_bf16_f32 v146, v146, v147
	v_cvt_pk_bf16_f32 v147, v148, v149
	v_add_u32_e32 v148, 0x800, v141
	ds_write2_b64 v148, v[144:145], v[146:147] offset0:32 offset1:36
	v_mul_f32_e32 v144, v102, v142
	v_mul_f32_e32 v145, v103, v142
	v_mul_f32_e32 v146, v104, v142
	v_mul_f32_e32 v147, v105, v142
	v_cvt_pk_bf16_f32 v144, v144, v145
	v_cvt_pk_bf16_f32 v145, v146, v147
	v_mul_f32_e32 v146, v98, v142
	v_mul_f32_e32 v147, v99, v142
	v_mul_f32_e32 v143, v101, v142
	v_mul_f32_e32 v142, v100, v142
	v_cvt_pk_bf16_f32 v146, v146, v147
	v_cvt_pk_bf16_f32 v147, v142, v143
	v_mov_b32_e32 v142, v151
	ds_write2_b64 v148, v[144:145], v[146:147] offset0:40 offset1:44
	s_waitcnt vmcnt(0)
	v_fmamk_f32 v142, v142, 0x3a800000, v188
	v_rsq_f32_e32 v142, v142
	s_nop 0
	v_mul_f32_e32 v142, v0, v142
	v_mul_f32_e32 v144, v94, v142
	v_mul_f32_e32 v145, v95, v142
	v_mul_f32_e32 v146, v96, v142
	v_mul_f32_e32 v147, v97, v142
	v_cvt_pk_bf16_f32 v144, v144, v145
	v_cvt_pk_bf16_f32 v145, v146, v147
	v_mul_f32_e32 v146, v90, v142
	v_mul_f32_e32 v147, v91, v142
	v_mul_f32_e32 v148, v92, v142
	v_mul_f32_e32 v149, v93, v142
	v_cvt_pk_bf16_f32 v146, v146, v147
	v_cvt_pk_bf16_f32 v147, v148, v149
	v_add_u32_e32 v148, 0x1000, v141
	ds_write2_b64 v148, v[144:145], v[146:147] offset0:64 offset1:68
	v_mul_f32_e32 v144, v86, v142
	v_mul_f32_e32 v145, v87, v142
	v_mul_f32_e32 v146, v88, v142
	v_mul_f32_e32 v147, v89, v142
	v_cvt_pk_bf16_f32 v144, v144, v145
	v_cvt_pk_bf16_f32 v145, v146, v147
	v_mul_f32_e32 v146, v82, v142
	v_mul_f32_e32 v147, v83, v142
	v_mul_f32_e32 v143, v85, v142
	v_mul_f32_e32 v142, v84, v142
	v_cvt_pk_bf16_f32 v146, v146, v147
	v_cvt_pk_bf16_f32 v147, v142, v143
	v_mov_b32_e32 v142, v152
	ds_write2_b64 v148, v[144:145], v[146:147] offset0:72 offset1:76
	s_waitcnt vmcnt(0)
	v_fmamk_f32 v142, v142, 0x3a800000, v188
	v_rsq_f32_e32 v142, v142
	s_nop 0
	v_mul_f32_e32 v142, v0, v142
	v_mul_f32_e32 v144, v78, v142
	v_mul_f32_e32 v145, v79, v142
	v_mul_f32_e32 v146, v80, v142
	v_mul_f32_e32 v147, v81, v142
	v_cvt_pk_bf16_f32 v144, v144, v145
	v_cvt_pk_bf16_f32 v145, v146, v147
	v_mul_f32_e32 v146, v74, v142
	v_mul_f32_e32 v147, v75, v142
	v_mul_f32_e32 v148, v76, v142
	v_mul_f32_e32 v149, v77, v142
	v_cvt_pk_bf16_f32 v146, v146, v147
	v_cvt_pk_bf16_f32 v147, v148, v149
	v_add_u32_e32 v148, 0x1800, v141
	ds_write2_b64 v148, v[144:145], v[146:147] offset0:96 offset1:100
	v_mul_f32_e32 v144, v70, v142
	v_mul_f32_e32 v145, v71, v142
	v_mul_f32_e32 v146, v72, v142
	v_mul_f32_e32 v147, v73, v142
	v_cvt_pk_bf16_f32 v144, v144, v145
	v_cvt_pk_bf16_f32 v145, v146, v147
	v_mul_f32_e32 v146, v66, v142
	v_mul_f32_e32 v147, v67, v142
	v_mul_f32_e32 v143, v69, v142
	v_mul_f32_e32 v142, v68, v142
	v_cvt_pk_bf16_f32 v146, v146, v147
	v_cvt_pk_bf16_f32 v147, v142, v143
	v_mov_b32_e32 v142, v153
	ds_write2_b64 v148, v[144:145], v[146:147] offset0:104 offset1:108
	s_waitcnt vmcnt(0)
; template <int EPI>
; DI void gemm_tile(const Params& p, int layer, int mt, int nt, u16* sm, int wv) {
;     ...
; #pragma unroll
;       for (int i = 0; i < 8; ++i) {
;         const int m = m0 + wm * 128 + 16 * i + fr;
;         const float rs = __builtin_amdgcn_rsqf(ssl[m] * (1.f / DM) + EPS) * qsc;
;         u16* d = stg + (16 * i + fr) * LSTR + 4 * fq;
; #pragma unroll
;         for (int j = 0; j < 4; ++j) {
;           u32x2 v = {pk2(acc[i][j][0] * rs, acc[i][j][1] * rs), pk2(acc[i][j][2] * rs, acc[i][j][3] * rs)};
;           *(u32x2*)(d + 16 * j) = v;
;         }
;       }
;       u16* gdst = p.proj + (size_t)(m0 + wm * 128) * DIN + n0 + wn * 64;
; #pragma unroll
;       for (int t = 0; t < 16; ++t) {
;         const int c = lane + 64 * t, row = c >> 3, kc = c & 7;
;         const u32x4 v = *(const u32x4*)(stg + row * LSTR + kc * 8);
;         *(u32x4*)(gdst + (size_t)row * DIN + kc * 8) = v;
;       }
	v_fmamk_f32 v142, v142, 0x3a800000, v188
	v_rsq_f32_e32 v142, v142
	s_nop 0
	v_mul_f32_e32 v142, v0, v142
	v_mul_f32_e32 v144, v62, v142
	v_mul_f32_e32 v145, v63, v142
	v_mul_f32_e32 v146, v64, v142
	v_mul_f32_e32 v147, v65, v142
	v_cvt_pk_bf16_f32 v144, v144, v145
	v_cvt_pk_bf16_f32 v145, v146, v147
	v_mul_f32_e32 v146, v58, v142
	v_mul_f32_e32 v147, v59, v142
	v_mul_f32_e32 v148, v60, v142
	v_mul_f32_e32 v149, v61, v142
	v_cvt_pk_bf16_f32 v146, v146, v147
	v_cvt_pk_bf16_f32 v147, v148, v149
	v_add_u32_e32 v148, 0x2000, v141
	ds_write2_b64 v148, v[144:145], v[146:147] offset0:128 offset1:132
	v_mul_f32_e32 v144, v54, v142
	v_mul_f32_e32 v145, v55, v142
	v_mul_f32_e32 v146, v56, v142
	v_mul_f32_e32 v147, v57, v142
	v_cvt_pk_bf16_f32 v144, v144, v145
	v_cvt_pk_bf16_f32 v145, v146, v147
	v_mul_f32_e32 v146, v50, v142
	v_mul_f32_e32 v147, v51, v142
	v_mul_f32_e32 v143, v53, v142
	v_mul_f32_e32 v142, v52, v142
	v_cvt_pk_bf16_f32 v146, v146, v147
	v_cvt_pk_bf16_f32 v147, v142, v143
	v_mov_b32_e32 v142, v154
	ds_write2_b64 v148, v[144:145], v[146:147] offset0:136 offset1:140
	s_waitcnt vmcnt(0)
	v_fmamk_f32 v142, v142, 0x3a800000, v188
	v_rsq_f32_e32 v142, v142
	s_nop 0
	v_mul_f32_e32 v142, v0, v142
	v_mul_f32_e32 v144, v46, v142
	v_mul_f32_e32 v145, v47, v142
	v_mul_f32_e32 v146, v48, v142
	v_mul_f32_e32 v147, v49, v142
	v_cvt_pk_bf16_f32 v144, v144, v145
	v_cvt_pk_bf16_f32 v145, v146, v147
	v_mul_f32_e32 v146, v42, v142
	v_mul_f32_e32 v147, v43, v142
	v_mul_f32_e32 v148, v44, v142
	v_mul_f32_e32 v149, v45, v142
	v_cvt_pk_bf16_f32 v146, v146, v147
	v_cvt_pk_bf16_f32 v147, v148, v149
	v_add_u32_e32 v148, 0x2800, v141
	ds_write2_b64 v148, v[144:145], v[146:147] offset0:160 offset1:164
	v_mul_f32_e32 v144, v38, v142
	v_mul_f32_e32 v145, v39, v142
	v_mul_f32_e32 v146, v40, v142
	v_mul_f32_e32 v147, v41, v142
	v_cvt_pk_bf16_f32 v144, v144, v145
	v_cvt_pk_bf16_f32 v145, v146, v147
	v_mul_f32_e32 v146, v34, v142
	v_mul_f32_e32 v147, v35, v142
	v_mul_f32_e32 v143, v37, v142
	v_mul_f32_e32 v142, v36, v142
	v_cvt_pk_bf16_f32 v146, v146, v147
	v_cvt_pk_bf16_f32 v147, v142, v143
	v_mov_b32_e32 v142, v155
	ds_write2_b64 v148, v[144:145], v[146:147] offset0:168 offset1:172
	v_mov_b32_e32 v132, v156
	s_waitcnt vmcnt(1)
	v_fmamk_f32 v142, v142, 0x3a800000, v188
	v_rsq_f32_e32 v142, v142
	s_waitcnt vmcnt(0)
	v_fmamk_f32 v132, v132, 0x3a800000, v188
	v_rsq_f32_e32 v132, v132
	v_mul_f32_e32 v142, v0, v142
	v_mul_f32_e32 v144, v30, v142
	v_mul_f32_e32 v145, v31, v142
	v_mul_f32_e32 v146, v32, v142
	v_mul_f32_e32 v147, v33, v142
	v_cvt_pk_bf16_f32 v144, v144, v145
	v_cvt_pk_bf16_f32 v145, v146, v147
	v_mul_f32_e32 v146, v26, v142
	v_mul_f32_e32 v147, v27, v142
	v_mul_f32_e32 v148, v28, v142
	v_mul_f32_e32 v149, v29, v142
	v_cvt_pk_bf16_f32 v146, v146, v147
	v_cvt_pk_bf16_f32 v147, v148, v149
	v_add_u32_e32 v148, 0x3000, v141
	ds_write2_b64 v148, v[144:145], v[146:147] offset0:192 offset1:196
	v_mul_f32_e32 v144, v22, v142
	v_mul_f32_e32 v145, v23, v142
	v_mul_f32_e32 v146, v24, v142
	v_mul_f32_e32 v147, v25, v142
	v_cvt_pk_bf16_f32 v144, v144, v145
	v_cvt_pk_bf16_f32 v145, v146, v147
	v_mul_f32_e32 v146, v18, v142
	v_mul_f32_e32 v147, v19, v142
	v_mul_f32_e32 v143, v21, v142
	v_mul_f32_e32 v142, v20, v142
	v_mul_f32_e32 v0, v0, v132
	v_cvt_pk_bf16_f32 v146, v146, v147
	v_cvt_pk_bf16_f32 v147, v142, v143
	v_mul_f32_e32 v132, v14, v0
	v_mul_f32_e32 v133, v15, v0
	v_mul_f32_e32 v142, v16, v0
	v_mul_f32_e32 v143, v17, v0
	ds_write2_b64 v148, v[144:145], v[146:147] offset0:200 offset1:204
	v_cvt_pk_bf16_f32 v132, v132, v133
	v_cvt_pk_bf16_f32 v133, v142, v143
	v_mul_f32_e32 v142, v6, v0
	v_mul_f32_e32 v143, v7, v0
	v_mul_f32_e32 v144, v8, v0
	v_mul_f32_e32 v145, v9, v0
	v_cvt_pk_bf16_f32 v142, v142, v143
	v_cvt_pk_bf16_f32 v143, v144, v145
	v_add_u32_e32 v141, 0x3800, v141
	ds_write2_b64 v141, v[132:133], v[142:143] offset0:224 offset1:228
	v_mul_f32_e32 v132, v2, v0
	v_mul_f32_e32 v133, v3, v0
	v_mul_f32_e32 v142, v4, v0
	v_mul_f32_e32 v143, v5, v0
	v_cvt_pk_bf16_f32 v132, v132, v133
	v_cvt_pk_bf16_f32 v133, v142, v143
	v_mul_f32_e32 v142, v10, v0
	v_mul_f32_e32 v143, v11, v0
	v_mul_f32_e32 v144, v12, v0
	v_mul_f32_e32 v145, v13, v0
	v_cvt_pk_bf16_f32 v142, v142, v143
	v_cvt_pk_bf16_f32 v143, v144, v145
	ds_write2_b64 v141, v[132:133], v[142:143] offset0:232 offset1:236
	v_mov_b64_e32 v[132:133], s[62:63]
	v_mad_i64_i32 v[132:133], s[4:5], v139, s8, v[132:133]
	v_lshl_add_u64 v[132:133], s[2:3], 1, v[132:133]
	v_lshlrev_b32_e32 v0, 7, v131
	v_lshrrev_b32_e32 v148, 3, v140
	v_lshl_add_u64 v[132:133], v[132:133], 0, v[0:1]
	v_and_b32_e32 v0, 0x70, v136
	v_mul_u32_u24_e32 v140, 0x90, v148
	v_add3_u32 v149, v135, v0, v140
	ds_read_b128 v[206:209], v149
	ds_read_b128 v[210:213], v149 offset:1152
	ds_read_b128 v[214:217], v149 offset:2304
	ds_read_b128 v[218:221], v149 offset:3456
	ds_read_b128 v[222:225], v149 offset:4608
	ds_read_b128 v[228:231], v149 offset:5760
	ds_read_b128 v[232:235], v149 offset:6912
	ds_read_b128 v[236:239], v149 offset:8064
	v_lshl_add_u64 v[132:133], v[132:133], 0, v[0:1]
	v_mul_u32_u24_e32 v0, 0xd00, v148
	v_lshlrev_b32_e32 v0, 1, v0
	v_lshl_add_u64 v[144:145], v[132:133], 0, v[0:1]
	s_cmp_eq_u32 s40, 2
	s_cbranch_scc1 .Lepi_hi_skip
	s_waitcnt lgkmcnt(7)
	global_store_dwordx4 v[144:145], v[206:209], off sc1
	s_mov_b32 s2, 0xd000
	v_add_co_u32_e32 v146, vcc, s2, v144
	s_mov_b32 s2, 0x1a000
	s_nop 0
	v_addc_co_u32_e32 v147, vcc, 0, v145, vcc
	s_waitcnt lgkmcnt(6)
	global_store_dwordx4 v[146:147], v[210:213], off sc1
	v_add_co_u32_e32 v146, vcc, s2, v144
	s_mov_b32 s2, 0x27000
	s_nop 0
	v_addc_co_u32_e32 v147, vcc, 0, v145, vcc
	s_waitcnt lgkmcnt(5)
	global_store_dwordx4 v[146:147], v[214:217], off sc1
	v_add_co_u32_e32 v144, vcc, s2, v144
	s_movk_i32 s2, 0xd00
	s_nop 0
	v_addc_co_u32_e32 v145, vcc, 0, v145, vcc
	s_waitcnt lgkmcnt(4)
	global_store_dwordx4 v[144:145], v[218:221], off sc1
	v_add_u32_e32 v144, 0x34000, v0
	v_mov_b32_e32 v145, v1
	v_lshl_add_u64 v[144:145], v[132:133], 0, v[144:145]
	s_waitcnt lgkmcnt(3)
	global_store_dwordx4 v[144:145], v[222:225], off sc1
	v_add_u32_e32 v144, 0x41000, v0
	v_mov_b32_e32 v145, v1
	v_lshl_add_u64 v[144:145], v[132:133], 0, v[144:145]
	s_waitcnt lgkmcnt(2)
	global_store_dwordx4 v[144:145], v[228:231], off sc1
	v_add_u32_e32 v144, 0x4e000, v0
	v_mov_b32_e32 v145, v1
	v_lshl_add_u64 v[144:145], v[132:133], 0, v[144:145]
	s_waitcnt lgkmcnt(1)
	global_store_dwordx4 v[144:145], v[232:235], off sc1
	v_add_u32_e32 v144, 0x5b000, v0
	v_mov_b32_e32 v145, v1
	v_lshl_add_u64 v[144:145], v[132:133], 0, v[144:145]
	s_waitcnt lgkmcnt(0)
	global_store_dwordx4 v[144:145], v[236:239], off sc1
	s_cmp_eq_u32 s40, 1
	s_cbranch_scc1 .Lgx_halfdone
	s_branch .Lepi_t8

; template <int EPI>
; DI void gemm_tile(const Params& p, int layer, int mt, int nt, u16* sm, int wv) {
;     ...
; #pragma unroll
;       for (int t = 0; t < 16; ++t) {
;         const int c = lane + 64 * t, row = c >> 3, kc = c & 7;
;         const u32x4 v = *(const u32x4*)(stg + row * LSTR + kc * 8);
;         *(u32x4*)(gdst + (size_t)row * DIN + kc * 8) = v;
;       }
.Lepi_t8:
	ds_read_b128 v[206:209], v149 offset:9216
	ds_read_b128 v[210:213], v149 offset:10368
	ds_read_b128 v[214:217], v149 offset:11520
	ds_read_b128 v[218:221], v149 offset:12672
	ds_read_b128 v[222:225], v149 offset:13824
	ds_read_b128 v[228:231], v149 offset:14976
	ds_read_b128 v[232:235], v149 offset:16128
	v_add_u32_e32 v144, 0x68000, v0
	v_mov_b32_e32 v145, v1
	v_lshl_add_u64 v[144:145], v[132:133], 0, v[144:145]
	s_waitcnt lgkmcnt(6)
	global_store_dwordx4 v[144:145], v[206:209], off sc1
	v_add_u32_e32 v144, 0x75000, v0
	v_mov_b32_e32 v145, v1
	v_lshl_add_u64 v[144:145], v[132:133], 0, v[144:145]
	s_waitcnt lgkmcnt(5)
	global_store_dwordx4 v[144:145], v[210:213], off sc1
	v_add_u32_e32 v144, 0x82000, v0
	v_mov_b32_e32 v145, v1
	v_lshl_add_u64 v[144:145], v[132:133], 0, v[144:145]
	s_waitcnt lgkmcnt(4)
	global_store_dwordx4 v[144:145], v[214:217], off sc1
	v_add_u32_e32 v144, 0x8f000, v0
	v_mov_b32_e32 v145, v1
	v_lshl_add_u64 v[144:145], v[132:133], 0, v[144:145]
	s_waitcnt lgkmcnt(3)
	global_store_dwordx4 v[144:145], v[218:221], off sc1
	v_add_u32_e32 v144, 0x9c000, v0
	v_mov_b32_e32 v145, v1
	v_lshl_add_u64 v[144:145], v[132:133], 0, v[144:145]
	s_waitcnt lgkmcnt(2)
	global_store_dwordx4 v[144:145], v[222:225], off sc1
	v_add_u32_e32 v144, 0xa9000, v0
	v_mov_b32_e32 v145, v1
	v_lshl_add_u64 v[144:145], v[132:133], 0, v[144:145]
	v_add_u32_e32 v0, 0xb6000, v0
	s_waitcnt lgkmcnt(1)
	global_store_dwordx4 v[144:145], v[228:231], off sc1
	v_lshl_add_u64 v[144:145], v[132:133], 0, v[0:1]
	v_mad_u32_u24 v0, v148, s2, v193
	s_waitcnt lgkmcnt(0)
	global_store_dwordx4 v[144:145], v[232:235], off sc1
	s_nop 1
	v_add_u32_e32 v140, 0x4380, v149

; DI float bflo(unsigned v) { return __uint_as_float(v << 16); }
; DI float bfhi(unsigned v) { return __uint_as_float(v & 0xffff0000u); }
; __global__ void __launch_bounds__(256, 2) hymba_mega(Params p) {
;     ...
;     for (int row0 = (bid * 4 + (tid >> 6)) * 4; row0 < MTOK; row0 += nb * 16) {
;       f32x4 xv[4][4];
;       float rs[4];
; #pragma unroll
;       for (int q = 0; q < 4; ++q) {
;         rs[q] = ssf[row0 + q];
; #pragma unroll
;         for (int j = 0; j < 4; ++j) {
;           const u32x2 xb = __builtin_nontemporal_load((const u32x2*)((const u16*)p.x2 + (size_t)(row0 + q) * DM + j * 256 + lane * 4));
;           xv[q][j][0] = bflo(xb[0]); xv[q][j][1] = bfhi(xb[0]); xv[q][j][2] = bflo(xb[1]); xv[q][j][3] = bfhi(xb[1]);
;         }
;       }
; #pragma unroll
;       for (int q = 0; q < 4; ++q) {
;         const float rq = __builtin_amdgcn_rsqf(rs[q] * (1.f / DM) + EPS);
; #pragma unroll
;         for (int j = 0; j < 4; ++j) {
;           f32x4 v = xv[q][j];
;           v[0] *= rq * gv[j][0]; v[1] *= rq * gv[j][1]; v[2] *= rq * gv[j][2]; v[3] *= rq * gv[j][3];
.Lfin_loop:
	v_add_co_u32_e32 v38, vcc, s8, v24
	v_add_u32_e32 v20, s12, v20
	s_nop 0
	v_addc_co_u32_e32 v39, vcc, 0, v25, vcc
	v_add_co_u32_e32 v40, vcc, s9, v24
	v_lshl_add_u64 v[22:23], v[22:23], 0, s[0:1]
	s_nop 0
	v_addc_co_u32_e32 v41, vcc, 0, v25, vcc
	v_add_co_u32_e32 v94, vcc, s10, v24
	v_lshl_add_u64 v[26:27], v[26:27], 0, s[4:5]
	s_nop 0
	v_addc_co_u32_e32 v95, vcc, 0, v25, vcc
	v_cmp_lt_i32_e32 vcc, s11, v20
	s_or_b64 s[6:7], vcc, s[6:7]
	s_mov_b64 s[14:15], exec
	s_andn2_b64 exec, exec, s[6:7]
	global_load_dwordx4 v[236:239], v[22:23], off
	global_load_dwordx2 v[200:201], v[26:27], off offset:-4096 nt
	global_load_dwordx2 v[202:203], v[26:27], off offset:-3584 nt
	global_load_dwordx2 v[204:205], v[26:27], off offset:-3072 nt
	global_load_dwordx2 v[206:207], v[26:27], off offset:-2560 nt
	global_load_dwordx2 v[208:209], v[26:27], off offset:-2048 nt
	global_load_dwordx2 v[210:211], v[26:27], off offset:-1536 nt
	global_load_dwordx2 v[212:213], v[26:27], off offset:-1024 nt
	global_load_dwordx2 v[214:215], v[26:27], off offset:-512 nt
	global_load_dwordx2 v[216:217], v[26:27], off nt
	global_load_dwordx2 v[218:219], v[26:27], off offset:512 nt
	global_load_dwordx2 v[220:221], v[26:27], off offset:1024 nt
	global_load_dwordx2 v[222:223], v[26:27], off offset:1536 nt
	global_load_dwordx2 v[224:225], v[26:27], off offset:2048 nt
	global_load_dwordx2 v[226:227], v[26:27], off offset:2560 nt
	global_load_dwordx2 v[228:229], v[26:27], off offset:3072 nt
	global_load_dwordx2 v[230:231], v[26:27], off offset:3584 nt
	s_mov_b64 exec, s[14:15]
	s_waitcnt vmcnt(33)
	v_fmamk_f32 v16, v16, 0x3a800000, v21
	v_fmamk_f32 v17, v17, 0x3a800000, v21
	v_fmamk_f32 v19, v19, 0x3a800000, v21
	v_rsq_f32_e32 v16, v16
	s_waitcnt vmcnt(32)
	v_lshlrev_b32_e32 v64, 16, v62
	v_and_b32_e32 v65, 0xffff0000, v62
	v_lshlrev_b32_e32 v62, 16, v63
	v_and_b32_e32 v63, 0xffff0000, v63
	s_waitcnt vmcnt(25)
	v_lshlrev_b32_e32 v80, 16, v48
	v_and_b32_e32 v81, 0xffff0000, v48
	v_fmamk_f32 v48, v18, 0x3a800000, v21
	v_rsq_f32_e32 v18, v17
	v_lshlrev_b32_e32 v66, 16, v60
	s_waitcnt vmcnt(20)
	v_lshlrev_b32_e32 v100, 16, v34
	v_and_b32_e32 v101, 0xffff0000, v34
	s_waitcnt vmcnt(18)
	v_lshlrev_b32_e32 v108, 16, v30
	v_and_b32_e32 v109, 0xffff0000, v30
	s_waitcnt vmcnt(17)
	v_lshlrev_b32_e32 v112, 16, v28
	v_and_b32_e32 v113, 0xffff0000, v28
	v_rsq_f32_e32 v28, v48
	v_rsq_f32_e32 v30, v19
	v_lshlrev_b32_e32 v102, 16, v35
	v_and_b32_e32 v103, 0xffff0000, v35
	v_lshlrev_b32_e32 v104, 16, v32
	v_and_b32_e32 v105, 0xffff0000, v32
	v_lshlrev_b32_e32 v106, 16, v33
	v_and_b32_e32 v107, 0xffff0000, v33
	v_mul_f32_e32 v32, v16, v12
	v_mul_f32_e32 v33, v16, v13
	v_mul_f32_e32 v34, v16, v14
	v_mul_f32_e32 v35, v16, v15
	v_and_b32_e32 v67, 0xffff0000, v60
	v_lshlrev_b32_e32 v60, 16, v61
	v_and_b32_e32 v61, 0xffff0000, v61
	v_lshlrev_b32_e32 v68, 16, v58
	v_and_b32_e32 v69, 0xffff0000, v58
	v_lshlrev_b32_e32 v58, 16, v59
	v_and_b32_e32 v59, 0xffff0000, v59
	v_lshlrev_b32_e32 v70, 16, v56
	v_and_b32_e32 v71, 0xffff0000, v56
	v_lshlrev_b32_e32 v56, 16, v57
	v_and_b32_e32 v57, 0xffff0000, v57
	v_lshlrev_b32_e32 v72, 16, v54
	v_and_b32_e32 v73, 0xffff0000, v54
	v_lshlrev_b32_e32 v54, 16, v55
	v_and_b32_e32 v55, 0xffff0000, v55
	v_lshlrev_b32_e32 v74, 16, v52
	v_and_b32_e32 v75, 0xffff0000, v52
	v_lshlrev_b32_e32 v52, 16, v53
	v_and_b32_e32 v53, 0xffff0000, v53
	v_lshlrev_b32_e32 v76, 16, v50
	v_and_b32_e32 v77, 0xffff0000, v50
	v_lshlrev_b32_e32 v78, 16, v51
	v_and_b32_e32 v79, 0xffff0000, v51
	v_lshlrev_b32_e32 v82, 16, v49
	v_and_b32_e32 v83, 0xffff0000, v49
	v_lshlrev_b32_e32 v84, 16, v46
	v_and_b32_e32 v85, 0xffff0000, v46
	v_lshlrev_b32_e32 v86, 16, v47
	v_and_b32_e32 v87, 0xffff0000, v47
	v_lshlrev_b32_e32 v88, 16, v44
	v_and_b32_e32 v89, 0xffff0000, v44
	v_lshlrev_b32_e32 v90, 16, v45
	v_and_b32_e32 v91, 0xffff0000, v45
	v_lshlrev_b32_e32 v92, 16, v42
	v_and_b32_e32 v93, 0xffff0000, v42
	v_lshlrev_b32_e32 v96, 16, v43
	v_and_b32_e32 v97, 0xffff0000, v43
	v_lshlrev_b32_e32 v98, 16, v36
	v_and_b32_e32 v99, 0xffff0000, v36
	v_lshlrev_b32_e32 v36, 16, v37
	v_and_b32_e32 v37, 0xffff0000, v37
	v_lshlrev_b32_e32 v110, 16, v31
	v_and_b32_e32 v111, 0xffff0000, v31
	v_lshlrev_b32_e32 v114, 16, v29
	v_and_b32_e32 v115, 0xffff0000, v29
	v_mul_f32_e32 v42, v16, v8
	v_mul_f32_e32 v43, v16, v9
	v_mul_f32_e32 v44, v16, v10
	v_mul_f32_e32 v45, v16, v11
	v_mul_f32_e32 v46, v16, v4
	v_mul_f32_e32 v47, v16, v5
	v_mul_f32_e32 v48, v16, v6
	v_mul_f32_e32 v49, v16, v7
	v_mul_f32_e32 v50, v16, v0
	v_mul_f32_e32 v51, v16, v1
	v_mul_f32_e32 v116, v16, v2
	v_mul_f32_e32 v117, v16, v3
	v_mul_f32_e32 v118, v18, v12
	v_mul_f32_e32 v119, v18, v13
	v_mul_f32_e32 v120, v18, v14
	v_mul_f32_e32 v121, v18, v15
	v_mul_f32_e32 v122, v18, v8
	v_mul_f32_e32 v123, v18, v9
	v_mul_f32_e32 v124, v18, v10
	v_mul_f32_e32 v125, v18, v11
	v_mul_f32_e32 v126, v18, v4
	v_mul_f32_e32 v127, v18, v5
	v_mul_f32_e32 v128, v18, v6
	v_mul_f32_e32 v129, v18, v7
	v_mul_f32_e32 v130, v18, v0
; __global__ void __launch_bounds__(256, 2) hymba_mega(Params p) {
;     ...
;       for (int q = 0; q < 4; ++q) {
;         const float rq = __builtin_amdgcn_rsqf(rs[q] * (1.f / DM) + EPS);
; #pragma unroll
;         for (int j = 0; j < 4; ++j) {
;           f32x4 v = xv[q][j];
;           v[0] *= rq * gv[j][0]; v[1] *= rq * gv[j][1]; v[2] *= rq * gv[j][2]; v[3] *= rq * gv[j][3];
;           __builtin_nontemporal_store(v, (f32x4*)(p.out + (size_t)(row0 + q) * DM + j * 256 + lane * 4));
;         }
;       }
;     }
	v_mul_f32_e32 v131, v18, v1
	v_mul_f32_e32 v132, v18, v2
	v_mul_f32_e32 v133, v18, v3
	v_mul_f32_e32 v134, v28, v12
	v_mul_f32_e32 v135, v28, v13
	v_mul_f32_e32 v136, v28, v14
	v_mul_f32_e32 v137, v28, v15
	v_mul_f32_e32 v138, v28, v8
	v_mul_f32_e32 v139, v28, v9
	v_mul_f32_e32 v140, v28, v10
	v_mul_f32_e32 v141, v28, v11
	v_mul_f32_e32 v142, v28, v4
	v_mul_f32_e32 v143, v28, v5
	v_mul_f32_e32 v144, v28, v6
	v_mul_f32_e32 v145, v28, v7
	v_mul_f32_e32 v146, v28, v0
	v_mul_f32_e32 v147, v28, v1
	v_mul_f32_e32 v148, v28, v2
	v_mul_f32_e32 v149, v28, v3
	v_mul_f32_e32 v150, v30, v12
	v_mul_f32_e32 v151, v30, v13
	v_mul_f32_e32 v152, v30, v14
	v_mul_f32_e32 v153, v30, v15
	v_mul_f32_e32 v154, v30, v8
	v_mul_f32_e32 v155, v30, v9
	v_mul_f32_e32 v156, v30, v10
	v_mul_f32_e32 v157, v30, v11
	v_mul_f32_e32 v158, v30, v4
	v_mul_f32_e32 v159, v30, v5
	v_mul_f32_e32 v160, v30, v6
	v_mul_f32_e32 v161, v30, v7
	v_mul_f32_e32 v162, v30, v0
	v_mul_f32_e32 v163, v30, v1
	v_mul_f32_e32 v164, v30, v2
	v_mul_f32_e32 v165, v30, v3
	v_mul_f32_e32 v16, v32, v64
	v_mul_f32_e32 v17, v33, v65
	v_mul_f32_e32 v18, v34, v62
	v_mul_f32_e32 v19, v35, v63
	v_mul_f32_e32 v28, v42, v66
	v_mul_f32_e32 v29, v43, v67
	v_mul_f32_e32 v30, v44, v60
	v_mul_f32_e32 v31, v45, v61
	v_mul_f32_e32 v32, v46, v68
	v_mul_f32_e32 v33, v47, v69
	v_mul_f32_e32 v34, v48, v58
	v_mul_f32_e32 v35, v49, v59
	v_mul_f32_e32 v42, v50, v70
	v_mul_f32_e32 v43, v51, v71
	v_mul_f32_e32 v44, v116, v56
	v_mul_f32_e32 v45, v117, v57
	v_mul_f32_e32 v46, v118, v72
	v_mul_f32_e32 v47, v119, v73
	v_mul_f32_e32 v48, v120, v54
	v_mul_f32_e32 v49, v121, v55
	v_mul_f32_e32 v50, v122, v74
	v_mul_f32_e32 v51, v123, v75
	v_mul_f32_e32 v52, v124, v52
	v_mul_f32_e32 v53, v125, v53
	v_mul_f32_e32 v54, v126, v76
	v_mul_f32_e32 v55, v127, v77
	v_mul_f32_e32 v56, v128, v78
	v_mul_f32_e32 v57, v129, v79
	v_mul_f32_e32 v58, v130, v80
	v_mul_f32_e32 v59, v131, v81
	v_mul_f32_e32 v60, v132, v82
	v_mul_f32_e32 v61, v133, v83
	v_mul_f32_e32 v62, v134, v84
	v_mul_f32_e32 v63, v135, v85
	v_mul_f32_e32 v64, v136, v86
	v_mul_f32_e32 v65, v137, v87
	v_mul_f32_e32 v66, v138, v88
	v_mul_f32_e32 v67, v139, v89
	v_mul_f32_e32 v68, v140, v90
	v_mul_f32_e32 v69, v141, v91
	v_mul_f32_e32 v70, v142, v92
	v_mul_f32_e32 v71, v143, v93
	v_mul_f32_e32 v72, v144, v96
	v_mul_f32_e32 v73, v145, v97
	v_mul_f32_e32 v74, v146, v98
	v_mul_f32_e32 v75, v147, v99
	v_mul_f32_e32 v76, v148, v36
	v_mul_f32_e32 v77, v149, v37
	v_mul_f32_e32 v78, v150, v100
	v_mul_f32_e32 v79, v151, v101
	v_mul_f32_e32 v80, v152, v102
	v_mul_f32_e32 v81, v153, v103
	v_mul_f32_e32 v82, v154, v104
	v_mul_f32_e32 v83, v155, v105
	v_mul_f32_e32 v84, v156, v106
	v_mul_f32_e32 v85, v157, v107
	v_mul_f32_e32 v86, v158, v108
	v_mul_f32_e32 v87, v159, v109
	v_mul_f32_e32 v88, v160, v110
	v_mul_f32_e32 v89, v161, v111
	v_mul_f32_e32 v90, v162, v112
	v_mul_f32_e32 v91, v163, v113
	v_mul_f32_e32 v92, v164, v114
	v_mul_f32_e32 v93, v165, v115
	global_store_dwordx4 v[24:25], v[16:19], off nt sc1
	global_store_dwordx4 v[24:25], v[28:31], off offset:1024 nt sc1
	global_store_dwordx4 v[24:25], v[32:35], off offset:2048 nt sc1
	global_store_dwordx4 v[24:25], v[42:45], off offset:3072 nt sc1
	global_store_dwordx4 v[40:41], v[46:49], off offset:-4096 nt sc1
	global_store_dwordx4 v[38:39], v[50:53], off offset:1024 nt sc1
	global_store_dwordx4 v[38:39], v[54:57], off offset:2048 nt sc1
	global_store_dwordx4 v[38:39], v[58:61], off offset:3072 nt sc1
	global_store_dwordx4 v[40:41], v[62:65], off nt sc1
	global_store_dwordx4 v[40:41], v[66:69], off offset:1024 nt sc1
	global_store_dwordx4 v[40:41], v[70:73], off offset:2048 nt sc1
	global_store_dwordx4 v[40:41], v[74:77], off offset:3072 nt sc1
	global_store_dwordx4 v[94:95], v[78:81], off nt sc1
	global_store_dwordx4 v[94:95], v[82:85], off offset:1024 nt sc1
	global_store_dwordx4 v[94:95], v[86:89], off offset:2048 nt sc1
	global_store_dwordx4 v[94:95], v[90:93], off offset:3072 nt sc1
	v_lshl_add_u64 v[24:25], v[24:25], 0, s[2:3]
	s_andn2_b64 exec, exec, s[6:7]
	s_cbranch_execz .LBB0_525
	s_waitcnt vmcnt(16)
	v_mov_b32_e32 v16, v236
	v_mov_b32_e32 v17, v237
	v_mov_b32_e32 v18, v238
	v_mov_b32_e32 v19, v239
	v_mov_b32_e32 v28, v230
	v_mov_b32_e32 v29, v231
	v_mov_b32_e32 v30, v228
	v_mov_b32_e32 v31, v229
	v_mov_b32_e32 v32, v226
	v_mov_b32_e32 v33, v227
	v_mov_b32_e32 v34, v224
	v_mov_b32_e32 v35, v225
	v_mov_b32_e32 v36, v222
	v_mov_b32_e32 v37, v223
	v_mov_b32_e32 v42, v220
	v_mov_b32_e32 v43, v221
	v_mov_b32_e32 v44, v218
	v_mov_b32_e32 v45, v219
	v_mov_b32_e32 v46, v216
	v_mov_b32_e32 v47, v217
	v_mov_b32_e32 v48, v214
	v_mov_b32_e32 v49, v215
	v_mov_b32_e32 v50, v212
	v_mov_b32_e32 v51, v213
	v_mov_b32_e32 v52, v210
	v_mov_b32_e32 v53, v211
	v_mov_b32_e32 v54, v208
	v_mov_b32_e32 v55, v209
	v_mov_b32_e32 v56, v206
	v_mov_b32_e32 v57, v207
	v_mov_b32_e32 v58, v204
	v_mov_b32_e32 v59, v205
	v_mov_b32_e32 v60, v202
	v_mov_b32_e32 v61, v203
	v_mov_b32_e32 v62, v200
	v_mov_b32_e32 v63, v201
	s_branch .Lfin_loop
